# speedup vs baseline: 1.0087x; 1.0046x over previous
; __device__ __forceinline__ unsigned cvt_pk_bf16(float lo, float hi) { unsigned r; asm volatile("v_cvt_pk_bf16_f32 %0, %1, %2" : "=v"(r) : "v"(lo), "v"(hi)); return r; }
; __device__ __forceinline__ float bflo(unsigned w) { return __uint_as_float(w << 16); }
; __device__ __forceinline__ float bfhi(unsigned w) { return __uint_as_float(w & 0xffff0000u); }
;     __device__ __forceinline__ void operator()(const f32x4 (&acc)[2][2][4][2], const Unit& u, int wr, int wc, int fr, int fq) const {
;         const int grow = rowoff + u.pm * 256; const bool lat = grow < MLAT; const int cond = lat ? (grow >> 13) : 8;
;         const float* bf = lat ? base_l + (size_t)grow * DM : base_c + (size_t)(grow - MLAT) * DM;
;         bf16_t* hp = hb + (size_t)grow * DM;
;         const int col0 = u.pn * 256 + wc * 32 + 8 * fq; const float* g = gate + cond * 6144 + col0;
;         f32x4 gv[2][2];
; #pragma unroll
;         for (int bj = 0; bj < 2; ++bj)
; #pragma unroll
;             for (int n = 0; n < 2; ++n) gv[bj][n] = *(const f32x4*)(g + bj * 128 + n * 4);
; #pragma unroll
;         for (int ai = 0; ai < 2; ++ai)
; #pragma unroll
;             for (int m = 0; m < 4; ++m) { const size_t off = (size_t)(wr * 64 + fr + ai * 128 + m * 16) * DM + col0;
; #pragma unroll
;                 for (int bj = 0; bj < 2; ++bj) { f32x4 b0, b1;
;                     if (BASE_F32) { b0 = *(const f32x4*)(bf + off + bj * 128); b1 = *(const f32x4*)(bf + off + bj * 128 + 4); }
;                     else { const u32x4 w = *(const u32x4*)(hp + off + bj * 128); b0 = (f32x4){bflo(w.x), bfhi(w.x), bflo(w.y), bfhi(w.y)}; b1 = (f32x4){bflo(w.z), bfhi(w.z), bflo(w.w), bfhi(w.w)}; }
;                     const f32x4 o0 = b0 + gv[bj][0] * acc[ai][bj][m][0], o1 = b1 + gv[bj][1] * acc[ai][bj][m][1]; u32x4 wo;
;                     wo.x = cvt_pk_bf16(o0[0], o0[1]); wo.y = cvt_pk_bf16(o0[2], o0[3]); wo.z = cvt_pk_bf16(o1[0], o1[1]); wo.w = cvt_pk_bf16(o1[2], o1[3]);
;                     *(u32x4*)(hp + off + bj * 128) = wo; } }
.LBB0_276:
	s_min_i32 s8, s14, 0x10000
	s_ashr_i32 s8, s8, 13
	s_mul_i32 s36, s8, 0x1800
	s_ashr_i32 s37, s36, 31
	s_lshl_b64 s[14:15], s[14:15], 11
	v_lshl_or_b32 v176, s66, 8, v180
	s_lshl_b64 s[36:37], s[36:37], 2
	s_add_u32 s36, s49, s36
	v_ashrrev_i32_e32 v177, 31, v176
	s_addc_u32 s37, s56, s37
	v_lshl_add_u64 v[192:193], v[152:153], 0, v[176:177]
	v_lshl_add_u64 v[132:133], v[176:177], 2, s[36:37]
	v_lshl_add_u64 v[194:195], v[192:193], 2, s[2:3]
	global_load_dwordx4 v[136:139], v[132:133], off
	global_load_dwordx4 v[184:187], v[194:195], off
	global_load_dwordx4 v[188:191], v[194:195], off offset:16
	global_load_dwordx4 v[140:143], v[132:133], off offset:16
	s_add_u32 s14, s68, s14
	s_addc_u32 s15, s69, s15
	v_lshl_add_u64 v[192:193], v[192:193], 1, s[14:15]
	global_load_dwordx4 v[128:131], v[132:133], off offset:528
	s_nop 0
	global_load_dwordx4 v[132:135], v[132:133], off offset:512
	s_andn2_b64 vcc, exec, s[6:7]
	v_lshl_add_u64 v[252:253], v[152:153], 0, v[176:177]
	v_lshl_add_u64 v[252:253], v[252:253], 2, s[2:3]
	global_load_dwordx4 v[212:215], v[252:253], off offset:512
	global_load_dwordx4 v[216:219], v[252:253], off offset:528
	v_lshl_add_u64 v[252:253], v[154:155], 0, v[176:177]
	v_lshl_add_u64 v[252:253], v[252:253], 2, s[2:3]
	global_load_dwordx4 v[220:223], v[252:253], off
	global_load_dwordx4 v[224:227], v[252:253], off offset:16
	v_lshl_add_u64 v[252:253], v[154:155], 0, v[176:177]
	v_lshl_add_u64 v[252:253], v[252:253], 2, s[2:3]
	global_load_dwordx4 v[228:231], v[252:253], off offset:512
	global_load_dwordx4 v[232:235], v[252:253], off offset:528
	v_lshl_add_u64 v[252:253], v[156:157], 0, v[176:177]
	v_lshl_add_u64 v[252:253], v[252:253], 2, s[2:3]
	global_load_dwordx4 v[236:239], v[252:253], off
	global_load_dwordx4 v[240:243], v[252:253], off offset:16
	v_lshl_add_u64 v[252:253], v[156:157], 0, v[176:177]
	v_lshl_add_u64 v[252:253], v[252:253], 2, s[2:3]
	global_load_dwordx4 v[244:247], v[252:253], off offset:512
	global_load_dwordx4 v[248:251], v[252:253], off offset:528
	v_lshl_add_u64 v[252:253], v[158:159], 0, v[176:177]
	v_lshl_add_u64 v[252:253], v[252:253], 2, s[2:3]
	global_load_dwordx4 v[196:199], v[252:253], off
	global_load_dwordx4 v[200:203], v[252:253], off offset:16
	s_waitcnt vmcnt(12)
	v_pk_fma_f32 v[124:125], v[124:125], v[136:137], v[184:185]
	v_pk_fma_f32 v[184:185], v[122:123], v[142:143], v[190:191]
	v_pk_fma_f32 v[122:123], v[120:121], v[140:141], v[188:189]
	v_pk_fma_f32 v[126:127], v[126:127], v[138:139], v[186:187]
	v_cvt_pk_bf16_f32 v120, v124, v125
	s_nop 0
	v_cvt_pk_bf16_f32 v121, v126, v127
	v_cvt_pk_bf16_f32 v122, v122, v123
	v_cvt_pk_bf16_f32 v123, v184, v185
	global_store_dwordx4 v[192:193], v[120:123], off
	s_nop 0
	v_lshl_add_u64 v[184:185], v[154:155], 0, v[176:177]
	v_lshl_add_u64 v[186:187], v[184:185], 2, s[2:3]
	s_waitcnt vmcnt(12)
	v_pk_fma_f32 v[112:113], v[112:113], v[132:133], v[212:213]
	s_waitcnt vmcnt(11)
	v_pk_fma_f32 v[120:121], v[106:107], v[130:131], v[218:219]
	v_pk_fma_f32 v[106:107], v[104:105], v[128:129], v[216:217]
	v_pk_fma_f32 v[114:115], v[114:115], v[134:135], v[214:215]
	v_cvt_pk_bf16_f32 v104, v112, v113
	s_nop 0
	v_cvt_pk_bf16_f32 v105, v114, v115
	v_cvt_pk_bf16_f32 v106, v106, v107
	v_cvt_pk_bf16_f32 v107, v120, v121
	global_store_dwordx4 v[192:193], v[104:107], off offset:256
	v_lshl_add_u64 v[252:253], v[158:159], 0, v[176:177]
	v_lshl_add_u64 v[252:253], v[252:253], 2, s[2:3]
	global_load_dwordx4 v[212:215], v[252:253], off offset:512
	global_load_dwordx4 v[216:219], v[252:253], off offset:528
	s_nop 0
	v_lshl_add_u64 v[120:121], v[184:185], 1, s[14:15]
	s_waitcnt vmcnt(13)
	v_pk_fma_f32 v[106:107], v[118:119], v[138:139], v[222:223]
	v_pk_fma_f32 v[104:105], v[116:117], v[136:137], v[220:221]
	s_waitcnt vmcnt(12)
	v_pk_fma_f32 v[110:111], v[110:111], v[142:143], v[226:227]
	v_pk_fma_f32 v[108:109], v[108:109], v[140:141], v[224:225]
	v_cvt_pk_bf16_f32 v104, v104, v105
	v_cvt_pk_bf16_f32 v105, v106, v107
	v_lshl_add_u64 v[112:113], v[156:157], 0, v[176:177]
	v_cvt_pk_bf16_f32 v106, v108, v109
	v_cvt_pk_bf16_f32 v107, v110, v111
	global_store_dwordx4 v[120:121], v[104:107], off
	v_lshl_add_u64 v[252:253], v[160:161], 0, v[176:177]
	v_lshl_add_u64 v[252:253], v[252:253], 2, s[2:3]
	global_load_dwordx4 v[220:223], v[252:253], off
	global_load_dwordx4 v[224:227], v[252:253], off offset:16
	s_nop 0
	v_lshl_add_u64 v[114:115], v[112:113], 2, s[2:3]
	s_waitcnt vmcnt(14)
	v_pk_fma_f32 v[96:97], v[96:97], v[132:133], v[228:229]
	s_waitcnt vmcnt(13)
	v_pk_fma_f32 v[104:105], v[90:91], v[130:131], v[234:235]
	v_pk_fma_f32 v[90:91], v[88:89], v[128:129], v[232:233]
	v_pk_fma_f32 v[98:99], v[98:99], v[134:135], v[230:231]
	v_cvt_pk_bf16_f32 v88, v96, v97
	s_nop 0
	v_cvt_pk_bf16_f32 v89, v98, v99
	v_cvt_pk_bf16_f32 v90, v90, v91
	v_cvt_pk_bf16_f32 v91, v104, v105
	global_store_dwordx4 v[120:121], v[88:91], off offset:256
	v_lshl_add_u64 v[252:253], v[160:161], 0, v[176:177]
	v_lshl_add_u64 v[252:253], v[252:253], 2, s[2:3]
	global_load_dwordx4 v[228:231], v[252:253], off offset:512
	global_load_dwordx4 v[232:235], v[252:253], off offset:528
	s_nop 0
	v_lshl_add_u64 v[104:105], v[112:113], 1, s[14:15]
	s_waitcnt vmcnt(15)
	v_pk_fma_f32 v[90:91], v[102:103], v[138:139], v[238:239]
	v_pk_fma_f32 v[88:89], v[100:101], v[136:137], v[236:237]
	s_waitcnt vmcnt(14)
; __device__ __forceinline__ unsigned cvt_pk_bf16(float lo, float hi) { unsigned r; asm volatile("v_cvt_pk_bf16_f32 %0, %1, %2" : "=v"(r) : "v"(lo), "v"(hi)); return r; }
; __device__ __forceinline__ float bflo(unsigned w) { return __uint_as_float(w << 16); }
; __device__ __forceinline__ float bfhi(unsigned w) { return __uint_as_float(w & 0xffff0000u); }
;     __device__ __forceinline__ void operator()(const f32x4 (&acc)[2][2][4][2], const Unit& u, int wr, int wc, int fr, int fq) const {
;     ...
;             for (int m = 0; m < 4; ++m) { const size_t off = (size_t)(wr * 64 + fr + ai * 128 + m * 16) * DM + col0;
; #pragma unroll
;                 for (int bj = 0; bj < 2; ++bj) { f32x4 b0, b1;
;                     if (BASE_F32) { b0 = *(const f32x4*)(bf + off + bj * 128); b1 = *(const f32x4*)(bf + off + bj * 128 + 4); }
;                     else { const u32x4 w = *(const u32x4*)(hp + off + bj * 128); b0 = (f32x4){bflo(w.x), bfhi(w.x), bflo(w.y), bfhi(w.y)}; b1 = (f32x4){bflo(w.z), bfhi(w.z), bflo(w.w), bfhi(w.w)}; }
;                     const f32x4 o0 = b0 + gv[bj][0] * acc[ai][bj][m][0], o1 = b1 + gv[bj][1] * acc[ai][bj][m][1]; u32x4 wo;
;                     wo.x = cvt_pk_bf16(o0[0], o0[1]); wo.y = cvt_pk_bf16(o0[2], o0[3]); wo.z = cvt_pk_bf16(o1[0], o1[1]); wo.w = cvt_pk_bf16(o1[2], o1[3]);
;                     *(u32x4*)(hp + off + bj * 128) = wo; } }
	v_pk_fma_f32 v[94:95], v[94:95], v[142:143], v[242:243]
	v_pk_fma_f32 v[92:93], v[92:93], v[140:141], v[240:241]
	v_cvt_pk_bf16_f32 v88, v88, v89
	v_cvt_pk_bf16_f32 v89, v90, v91
	v_lshl_add_u64 v[96:97], v[158:159], 0, v[176:177]
	v_cvt_pk_bf16_f32 v90, v92, v93
	v_cvt_pk_bf16_f32 v91, v94, v95
	global_store_dwordx4 v[104:105], v[88:91], off
	v_lshl_add_u64 v[252:253], v[162:163], 0, v[176:177]
	v_lshl_add_u64 v[252:253], v[252:253], 2, s[2:3]
	global_load_dwordx4 v[236:239], v[252:253], off
	global_load_dwordx4 v[240:243], v[252:253], off offset:16
	s_nop 0
	v_lshl_add_u64 v[98:99], v[96:97], 2, s[2:3]
	s_waitcnt vmcnt(16)
	v_pk_fma_f32 v[80:81], v[80:81], v[132:133], v[244:245]
	s_waitcnt vmcnt(15)
	v_pk_fma_f32 v[88:89], v[74:75], v[130:131], v[250:251]
	v_pk_fma_f32 v[74:75], v[72:73], v[128:129], v[248:249]
	v_pk_fma_f32 v[82:83], v[82:83], v[134:135], v[246:247]
	v_cvt_pk_bf16_f32 v72, v80, v81
	s_nop 0
	v_cvt_pk_bf16_f32 v73, v82, v83
	v_cvt_pk_bf16_f32 v74, v74, v75
	v_cvt_pk_bf16_f32 v75, v88, v89
	global_store_dwordx4 v[104:105], v[72:75], off offset:256
	v_lshl_add_u64 v[252:253], v[162:163], 0, v[176:177]
	v_lshl_add_u64 v[252:253], v[252:253], 2, s[2:3]
	global_load_dwordx4 v[244:247], v[252:253], off offset:512
	global_load_dwordx4 v[248:251], v[252:253], off offset:528
	s_nop 0
	v_lshl_add_u64 v[88:89], v[96:97], 1, s[14:15]
	s_waitcnt vmcnt(17)
	v_pk_fma_f32 v[74:75], v[86:87], v[138:139], v[198:199]
	v_pk_fma_f32 v[72:73], v[84:85], v[136:137], v[196:197]
	s_waitcnt vmcnt(16)
	v_pk_fma_f32 v[78:79], v[78:79], v[142:143], v[202:203]
	v_pk_fma_f32 v[76:77], v[76:77], v[140:141], v[200:201]
	v_cvt_pk_bf16_f32 v72, v72, v73
	v_cvt_pk_bf16_f32 v73, v74, v75
	v_lshl_add_u64 v[80:81], v[160:161], 0, v[176:177]
	v_cvt_pk_bf16_f32 v74, v76, v77
	v_cvt_pk_bf16_f32 v75, v78, v79
	global_store_dwordx4 v[88:89], v[72:75], off
	v_lshl_add_u64 v[252:253], v[164:165], 0, v[176:177]
	v_lshl_add_u64 v[252:253], v[252:253], 2, s[2:3]
	global_load_dwordx4 v[196:199], v[252:253], off
	global_load_dwordx4 v[200:203], v[252:253], off offset:16
	s_nop 0
	v_lshl_add_u64 v[82:83], v[80:81], 2, s[2:3]
	s_waitcnt vmcnt(16)
	v_pk_fma_f32 v[68:69], v[68:69], v[132:133], v[212:213]
	s_waitcnt vmcnt(15)
	v_pk_fma_f32 v[72:73], v[66:67], v[130:131], v[218:219]
	v_pk_fma_f32 v[66:67], v[64:65], v[128:129], v[216:217]
	v_pk_fma_f32 v[70:71], v[70:71], v[134:135], v[214:215]
	v_cvt_pk_bf16_f32 v64, v68, v69
	s_nop 0
	v_cvt_pk_bf16_f32 v65, v70, v71
	v_cvt_pk_bf16_f32 v66, v66, v67
	v_cvt_pk_bf16_f32 v67, v72, v73
	global_store_dwordx4 v[88:89], v[64:67], off offset:256
	v_lshl_add_u64 v[252:253], v[164:165], 0, v[176:177]
	v_lshl_add_u64 v[252:253], v[252:253], 2, s[2:3]
	global_load_dwordx4 v[212:215], v[252:253], off offset:512
	global_load_dwordx4 v[216:219], v[252:253], off offset:528
	s_nop 0
	v_lshl_add_u64 v[72:73], v[80:81], 1, s[14:15]
	s_waitcnt vmcnt(16)
	v_pk_fma_f32 v[60:61], v[60:61], v[136:137], v[220:221]
	s_waitcnt vmcnt(15)
	v_pk_fma_f32 v[64:65], v[58:59], v[142:143], v[226:227]
	v_pk_fma_f32 v[58:59], v[56:57], v[140:141], v[224:225]
	v_pk_fma_f32 v[62:63], v[62:63], v[138:139], v[222:223]
	v_cvt_pk_bf16_f32 v56, v60, v61
	s_nop 0
	v_cvt_pk_bf16_f32 v57, v62, v63
	v_cvt_pk_bf16_f32 v58, v58, v59
	v_cvt_pk_bf16_f32 v59, v64, v65
	global_store_dwordx4 v[72:73], v[56:59], off
	v_lshl_add_u64 v[252:253], v[166:167], 0, v[176:177]
	v_lshl_add_u64 v[252:253], v[252:253], 2, s[2:3]
	global_load_dwordx4 v[220:223], v[252:253], off
	global_load_dwordx4 v[224:227], v[252:253], off offset:16
	s_nop 0
	v_lshl_add_u64 v[64:65], v[162:163], 0, v[176:177]
	v_lshl_add_u64 v[66:67], v[64:65], 2, s[2:3]
	s_waitcnt vmcnt(16)
	v_pk_fma_f32 v[48:49], v[48:49], v[132:133], v[228:229]
	s_waitcnt vmcnt(15)
; __device__ __forceinline__ unsigned cvt_pk_bf16(float lo, float hi) { unsigned r; asm volatile("v_cvt_pk_bf16_f32 %0, %1, %2" : "=v"(r) : "v"(lo), "v"(hi)); return r; }
; __device__ __forceinline__ float bflo(unsigned w) { return __uint_as_float(w << 16); }
; __device__ __forceinline__ float bfhi(unsigned w) { return __uint_as_float(w & 0xffff0000u); }
;     __device__ __forceinline__ void operator()(const f32x4 (&acc)[2][2][4][2], const Unit& u, int wr, int wc, int fr, int fq) const {
;     ...
;             for (int m = 0; m < 4; ++m) { const size_t off = (size_t)(wr * 64 + fr + ai * 128 + m * 16) * DM + col0;
; #pragma unroll
;                 for (int bj = 0; bj < 2; ++bj) { f32x4 b0, b1;
;                     if (BASE_F32) { b0 = *(const f32x4*)(bf + off + bj * 128); b1 = *(const f32x4*)(bf + off + bj * 128 + 4); }
;                     else { const u32x4 w = *(const u32x4*)(hp + off + bj * 128); b0 = (f32x4){bflo(w.x), bfhi(w.x), bflo(w.y), bfhi(w.y)}; b1 = (f32x4){bflo(w.z), bfhi(w.z), bflo(w.w), bfhi(w.w)}; }
;                     const f32x4 o0 = b0 + gv[bj][0] * acc[ai][bj][m][0], o1 = b1 + gv[bj][1] * acc[ai][bj][m][1]; u32x4 wo;
;                     wo.x = cvt_pk_bf16(o0[0], o0[1]); wo.y = cvt_pk_bf16(o0[2], o0[3]); wo.z = cvt_pk_bf16(o1[0], o1[1]); wo.w = cvt_pk_bf16(o1[2], o1[3]);
;                     *(u32x4*)(hp + off + bj * 128) = wo; } }
	v_pk_fma_f32 v[56:57], v[42:43], v[130:131], v[234:235]
	v_pk_fma_f32 v[42:43], v[40:41], v[128:129], v[232:233]
	v_pk_fma_f32 v[50:51], v[50:51], v[134:135], v[230:231]
	v_cvt_pk_bf16_f32 v40, v48, v49
	s_nop 0
	v_cvt_pk_bf16_f32 v41, v50, v51
	v_cvt_pk_bf16_f32 v42, v42, v43
	v_cvt_pk_bf16_f32 v43, v56, v57
	global_store_dwordx4 v[72:73], v[40:43], off offset:256
	v_lshl_add_u64 v[252:253], v[166:167], 0, v[176:177]
	v_lshl_add_u64 v[252:253], v[252:253], 2, s[2:3]
	global_load_dwordx4 v[228:231], v[252:253], off offset:512
	global_load_dwordx4 v[232:235], v[252:253], off offset:528
	s_nop 0
	v_lshl_add_u64 v[56:57], v[64:65], 1, s[14:15]
	s_waitcnt vmcnt(16)
	v_pk_fma_f32 v[42:43], v[54:55], v[138:139], v[238:239]
	v_pk_fma_f32 v[40:41], v[52:53], v[136:137], v[236:237]
	s_waitcnt vmcnt(15)
	v_pk_fma_f32 v[46:47], v[46:47], v[142:143], v[242:243]
	v_pk_fma_f32 v[44:45], v[44:45], v[140:141], v[240:241]
	v_cvt_pk_bf16_f32 v40, v40, v41
	v_cvt_pk_bf16_f32 v41, v42, v43
	v_lshl_add_u64 v[48:49], v[164:165], 0, v[176:177]
	v_cvt_pk_bf16_f32 v42, v44, v45
	v_cvt_pk_bf16_f32 v43, v46, v47
	global_store_dwordx4 v[56:57], v[40:43], off
	s_nop 0
	v_lshl_add_u64 v[50:51], v[48:49], 2, s[2:3]
	s_waitcnt vmcnt(14)
	v_pk_fma_f32 v[32:33], v[32:33], v[132:133], v[244:245]
	s_waitcnt vmcnt(13)
	v_pk_fma_f32 v[40:41], v[26:27], v[130:131], v[250:251]
	v_pk_fma_f32 v[26:27], v[24:25], v[128:129], v[248:249]
	v_pk_fma_f32 v[34:35], v[34:35], v[134:135], v[246:247]
	v_cvt_pk_bf16_f32 v24, v32, v33
	s_nop 0
	v_cvt_pk_bf16_f32 v25, v34, v35
	v_cvt_pk_bf16_f32 v26, v26, v27
	v_cvt_pk_bf16_f32 v27, v40, v41
	global_store_dwordx4 v[56:57], v[24:27], off offset:256
	s_nop 0
	v_lshl_add_u64 v[40:41], v[48:49], 1, s[14:15]
	s_waitcnt vmcnt(12)
	v_pk_fma_f32 v[26:27], v[38:39], v[138:139], v[198:199]
	v_pk_fma_f32 v[24:25], v[36:37], v[136:137], v[196:197]
	s_waitcnt vmcnt(11)
	v_pk_fma_f32 v[30:31], v[30:31], v[142:143], v[202:203]
	v_pk_fma_f32 v[28:29], v[28:29], v[140:141], v[200:201]
	v_cvt_pk_bf16_f32 v24, v24, v25
	v_cvt_pk_bf16_f32 v25, v26, v27
	v_lshl_add_u64 v[32:33], v[166:167], 0, v[176:177]
	v_cvt_pk_bf16_f32 v26, v28, v29
	v_cvt_pk_bf16_f32 v27, v30, v31
	global_store_dwordx4 v[40:41], v[24:27], off
	s_nop 0
	v_lshl_add_u64 v[34:35], v[32:33], 2, s[2:3]
	s_mov_b64 s[2:3], -1
	s_waitcnt vmcnt(10)
	v_pk_fma_f32 v[16:17], v[16:17], v[132:133], v[212:213]
	s_waitcnt vmcnt(9)
	v_pk_fma_f32 v[24:25], v[10:11], v[130:131], v[218:219]
	v_pk_fma_f32 v[10:11], v[8:9], v[128:129], v[216:217]
	v_pk_fma_f32 v[18:19], v[18:19], v[134:135], v[214:215]
	v_cvt_pk_bf16_f32 v8, v16, v17
	s_nop 0
	v_cvt_pk_bf16_f32 v9, v18, v19
	v_cvt_pk_bf16_f32 v10, v10, v11
	v_cvt_pk_bf16_f32 v11, v24, v25
	global_store_dwordx4 v[40:41], v[8:11], off offset:256
	s_nop 0
	v_lshl_add_u64 v[24:25], v[32:33], 1, s[14:15]
	s_waitcnt vmcnt(8)
	v_pk_fma_f32 v[10:11], v[22:23], v[138:139], v[222:223]
	v_pk_fma_f32 v[8:9], v[20:21], v[136:137], v[220:221]
	s_waitcnt vmcnt(7)
	v_pk_fma_f32 v[14:15], v[14:15], v[142:143], v[226:227]
	v_pk_fma_f32 v[12:13], v[12:13], v[140:141], v[224:225]
	v_cvt_pk_bf16_f32 v8, v8, v9
	v_cvt_pk_bf16_f32 v9, v10, v11
	s_nop 0
	v_cvt_pk_bf16_f32 v10, v12, v13
	v_cvt_pk_bf16_f32 v11, v14, v15
	global_store_dwordx4 v[24:25], v[8:11], off
	s_nop 0
	s_waitcnt vmcnt(6)
	v_pk_fma_f32 v[4:5], v[4:5], v[132:133], v[228:229]
	s_waitcnt vmcnt(5)
	v_pk_fma_f32 v[8:9], v[2:3], v[130:131], v[234:235]
	v_pk_fma_f32 v[2:3], v[0:1], v[128:129], v[232:233]
	v_pk_fma_f32 v[6:7], v[6:7], v[134:135], v[230:231]
	v_cvt_pk_bf16_f32 v0, v4, v5
	s_nop 0
	v_cvt_pk_bf16_f32 v1, v6, v7
	v_cvt_pk_bf16_f32 v2, v2, v3
	v_cvt_pk_bf16_f32 v3, v8, v9
	global_store_dwordx4 v[24:25], v[0:3], off offset:256
	s_cbranch_vccnz .LBB0_265
	s_andn2_b64 vcc, exec, s[10:11]
	s_cbranch_vccnz .LBB0_264
	s_barrier
	s_branch .LBB0_264
